# phase start touches one dword per 4 KiB of the next GEMM phase's weight matrix (translation warm-up only, a few waves)
# speedup vs baseline: 1.0083x; 1.0083x over previous
; __global__ void __launch_bounds__(512, 2) mega_fwd(Args args) {
;     ...
;             const int q = ph - 1, c = q / PH_PER_CHUNK, r = q - c * PH_PER_CHUNK;
;             const bool is_prompt = c < 2;
;             float* X = args.out + (size_t)c * TC * D;
;             const int L = is_prompt ? 2048 : 8192;
;             bf16_t* xb = (bf16_t*)(ws + ((c & 1) ? WS_XB : WS_X16));
;             {
;                 const int l = r / 9, k = r - l * 9;
;                 const bf16_t* WL = Wb + (size_t)l * W_LAYER_ELEMS;
;                 if (k == 0 || k == 7) {
.LBB0_18:
	v_readfirstlane_b32 s24, v196
	s_lshr_b32 s1, s24, 6
	v_readlane_b32 s0, v254, 6
	s_mov_b32 s21, s20
	s_add_i32 s0, s0, s1
	v_and_b32_e32 v170, 63, v196
	v_writelane_b32 v255, s1, 42
	s_cmp_lg_u32 s21, 0
	s_mov_b64 s[8:9], -1
	s_cbranch_scc0 .LBB0_422
	s_add_i32 s1, s21, -1
	s_mul_hi_i32 s4, s1, 0x38e38e39
	s_lshr_b32 s5, s4, 31
	s_ashr_i32 s4, s4, 2
	s_add_i32 s30, s4, s5
	s_mul_i32 s4, s30, 0xffffffee
	s_add_i32 s5, s4, s1
	s_bitcmp0_b32 s30, 0
	s_mov_b32 s1, 0x1d800000
	s_cselect_b32 s1, s1, 0x9e00000
	s_add_u32 s76, s80, s1
	s_mul_hi_i32 s1, s5, 0x38e38e39
	s_addc_u32 s77, s81, 0
	s_lshr_b32 s4, s1, 31
	s_ashr_i32 s12, s1, 1
	s_add_i32 s12, s12, s4
	s_mul_i32 s1, s12, -9
	v_writelane_b32 v255, s5, 43
	s_add_i32 s1, s1, s5
	s_mul_i32 s5, s12, 0x3180000
	s_mul_hi_i32 s4, s12, 0x3180000
	s_add_u32 s5, s80, s5
	v_writelane_b32 v255, s5, 44
	s_addc_u32 s4, s81, s4
	v_writelane_b32 v255, s4, 45
	s_mov_b32 s8, 0
	s_mov_b32 s9, 0
	s_cmp_eq_u32 s1, 0
	s_cselect_b32 s8, 0x580000, s8
	s_cselect_b32 s9, 0xb00000, s9
	s_cmp_eq_u32 s1, 1
	s_cselect_b32 s8, 0xb80000, s8
	s_cselect_b32 s9, 0x1080000, s9
	s_cmp_eq_u32 s1, 4
	s_cselect_b32 s8, 0x300000, s8
	s_cselect_b32 s9, 0x1c00000, s9
	s_cmp_eq_u32 s1, 5
	s_cselect_b32 s8, 0x200000, s8
	s_cselect_b32 s9, 0x1f00000, s9
	s_cmp_eq_u32 s1, 6
	s_cselect_b32 s8, 0xb00000, s8
	s_cselect_b32 s9, 0x2100000, s9
	s_cmp_eq_u32 s1, 7
	s_cselect_b32 s8, 0x580000, s8
	s_cselect_b32 s9, 0x2c00000, s9
	s_cmp_eq_u32 s1, 8
	s_cselect_b32 s8, 0xb00000, s8
	s_cselect_b32 s9, 0x3180000, s9
	s_cmp_eq_u32 s8, 0
	s_cbranch_scc1 .Lwpf_skip
	s_lshr_b32 s38, s8, 18
	s_cmp_gt_u32 s0, s38
	s_cbranch_scc1 .Lwpf_skip
	s_mov_b32 s100, s5
	s_mov_b32 s101, s4
	s_cmp_eq_u32 s1, 8
	s_cselect_b32 s38, s12, 0
	s_cmp_eq_u32 s38, 1
	s_cselect_b32 s100, s80, s100
	s_cselect_b32 s101, s81, s101
	s_cselect_b32 s9, 0, s9
	v_lshl_add_u32 v1, s0, 6, v170
	v_lshlrev_b32_e32 v1, 12, v1
	v_cmp_gt_u32_e32 vcc, s8, v1
	v_add_u32_e32 v0, s9, v1
	s_lshr_b32 s8, s24, 6
	s_lshl_b32 s8, s8, 8
	s_add_i32 m0, s8, 0x20000
	s_and_saveexec_b64 s[38:39], vcc
	s_cbranch_execz .Lwpf_none
	global_load_lds_dword v0, s[100:101]
.Lwpf_none:
	s_mov_b64 exec, s[38:39]
